# attention kv loop software-pipelined across tiles (QK of tile t+1 inside softmax/PV of tile t, LDS double buffer, one barrier per tile)
# speedup vs baseline: 1.0227x; 1.0146x over previous
; __device__ __forceinline__ unsigned pack2(float a, float b) { unsigned r; asm("v_cvt_pk_bf16_f32 %0, %1, %2" : "=v"(r) : "v"(a), "v"(b)); return r; }
; __device__ __forceinline__ void phase_attn(CP& p, char* smem, int vid0, int grid) {
;     ...
;       const float mnew = mrun;
;       float psum = 0.f;
;       bf16x8 pf[4];
; #pragma unroll
;       for (int t2 = 0; t2 < 2; ++t2)
; #pragma unroll
;         for (int hf = 0; hf < 2; ++hf) {
;           union { unsigned u[4]; bf16x8 v; } cvp;
; #pragma unroll
;           for (int i = 0; i < 4; ++i) {
;             const float p0 = __builtin_amdgcn_exp2f(s[t2][hf * 8 + 2 * i] * cs - mnew);
;             const float p1 = __builtin_amdgcn_exp2f(s[t2][hf * 8 + 2 * i + 1] * cs - mnew);
;             psum += p0 + p1;
;             cvp.u[i] = pack2(p0, p1);
;           }
;           pf[t2 * 2 + hf] = cvp.v;
;         }
;       lrun += psum;
; #pragma unroll
;       for (int dt = 0; dt < 2; ++dt)
; #pragma unroll
;         for (int s4 = 0; s4 < 4; ++s4) {
;           const bf16x8 vfr = *(const bf16x8*)(Vs + (32 * dt + r) * 72 + 16 * s4 + 8 * hh);
;           oacc[dt] = __builtin_amdgcn_mfma_f32_32x32x16_bf16(vfr, pf[s4], oacc[dt], 0, 0, 0);
;         }
;     }
;     const float ltot = lrun + __shfl_xor(lrun, 32);
;     const float inv = 1.f / ltot;
;     bf16_t* op = p.hxc + xrow * 1024 + h * 64;
; #pragma unroll
;     for (int dt = 0; dt < 2; ++dt)
; #pragma unroll
;       for (int i4 = 0; i4 < 4; ++i4) {
;         const int d = 32 * dt + 8 * i4 + 4 * hh;
;         uint2 u; u.x = pack2(oacc[dt][4 * i4] * inv, oacc[dt][4 * i4 + 1] * inv); u.y = pack2(oacc[dt][4 * i4 + 2] * inv, oacc[dt][4 * i4 + 3] * inv);
;         *(uint2*)(op + d) = u;
;       }
;   }
.LBB0_2024:
	v_fma_f32 v3, v52, s25, -v147
	v_fma_f32 v52, v53, s25, -v147
	v_exp_f32_e32 v3, v3
	v_exp_f32_e32 v52, v52
	v_fma_f32 v36, v36, s25, -v147
	v_exp_f32_e32 v70, v36
	v_fma_f32 v36, v37, s25, -v147
	v_add_f32_e32 v53, v3, v52
	v_cvt_pk_bf16_f32 v52, v3, v52
	v_add_f32_e32 v3, 0, v53
	v_fma_f32 v53, v54, s25, -v147
	v_fma_f32 v54, v55, s25, -v147
	v_exp_f32_e32 v53, v53
	v_exp_f32_e32 v54, v54
	v_fma_f32 v55, v56, s25, -v147
	v_fma_f32 v56, v57, s25, -v147
	v_exp_f32_e32 v55, v55
	v_exp_f32_e32 v56, v56
	v_exp_f32_e32 v71, v36
	v_fma_f32 v36, v38, s25, -v147
	v_exp_f32_e32 v72, v36
	v_fma_f32 v36, v39, s25, -v147
	v_exp_f32_e32 v73, v36
	v_fma_f32 v36, v40, s25, -v147
	v_add_f32_e32 v57, v53, v54
	v_exp_f32_e32 v74, v36
	v_fma_f32 v36, v41, s25, -v147
	v_add_f32_e32 v3, v57, v3
	v_cvt_pk_bf16_f32 v53, v53, v54
	v_add_f32_e32 v54, v55, v56
	v_exp_f32_e32 v75, v36
	v_fma_f32 v36, v42, s25, -v147
	v_add_f32_e32 v3, v54, v3
	v_cvt_pk_bf16_f32 v54, v55, v56
	v_fma_f32 v55, v58, s25, -v147
	v_fma_f32 v56, v59, s25, -v147
	v_exp_f32_e32 v76, v36
	ds_read_b128 v[36:39], v146 offset:13312
	v_exp_f32_e32 v55, v55
	v_exp_f32_e32 v56, v56
	v_fma_f32 v57, v60, s25, -v147
	v_fma_f32 v58, v61, s25, -v147
	v_exp_f32_e32 v57, v57
	v_exp_f32_e32 v58, v58
	v_add_f32_e32 v59, v55, v56
	v_add_f32_e32 v3, v59, v3
	v_cvt_pk_bf16_f32 v55, v55, v56
	v_add_f32_e32 v56, v57, v58
	v_add_f32_e32 v3, v56, v3
	v_fma_f32 v56, v62, s25, -v147
	v_exp_f32_e32 v68, v56
	v_fma_f32 v56, v63, s25, -v147
	ds_read_b128 v[60:63], v146 offset:13344
	s_waitcnt lgkmcnt(1)
	v_mfma_f32_32x32x16_bf16 v[4:19], v[36:39], v[52:55], v[4:19]
	v_exp_f32_e32 v69, v56
	v_fma_f32 v56, v64, s25, -v147
	v_fma_f32 v36, v45, s25, -v147
	v_exp_f32_e32 v64, v56
	v_fma_f32 v56, v65, s25, -v147
	v_exp_f32_e32 v79, v36
	v_fma_f32 v36, v46, s25, -v147
	v_exp_f32_e32 v65, v56
	v_fma_f32 v56, v66, s25, -v147
	v_exp_f32_e32 v80, v36
	v_fma_f32 v36, v47, s25, -v147
	v_exp_f32_e32 v66, v56
	v_fma_f32 v56, v67, s25, -v147
	v_exp_f32_e32 v81, v36
	ds_read_b128 v[36:39], v146 offset:13376
	v_exp_f32_e32 v67, v56
	v_cvt_pk_bf16_f32 v56, v57, v58
	v_cvt_pk_bf16_f32 v57, v68, v69
	v_cvt_pk_bf16_f32 v58, v64, v65
	v_cvt_pk_bf16_f32 v59, v66, v67
	v_fma_f32 v44, v44, s25, -v147
	s_waitcnt lgkmcnt(1)
	v_mfma_f32_32x32x16_bf16 v[4:19], v[60:63], v[56:59], v[4:19]
	v_exp_f32_e32 v78, v44
	v_fma_f32 v44, v48, s25, -v147
	v_exp_f32_e32 v60, v44
	v_fma_f32 v44, v49, s25, -v147
	v_exp_f32_e32 v61, v44
	v_fma_f32 v44, v50, s25, -v147
	v_fma_f32 v40, v43, s25, -v147
	v_exp_f32_e32 v62, v44
	ds_read_b128 v[44:47], v146 offset:13408
	v_exp_f32_e32 v77, v40
	v_cvt_pk_bf16_f32 v40, v70, v71
	v_cvt_pk_bf16_f32 v41, v72, v73
	v_cvt_pk_bf16_f32 v42, v74, v75
	v_cvt_pk_bf16_f32 v43, v76, v77
	s_lshl_b32 s16, s16, 1
	s_waitcnt lgkmcnt(1)
	v_mfma_f32_32x32x16_bf16 v[4:19], v[36:39], v[40:43], v[4:19]
	v_fma_f32 v36, v51, s25, -v147
	ds_read_b128 v[48:51], v146 offset:17920
	v_exp_f32_e32 v63, v36
	v_cvt_pk_bf16_f32 v36, v78, v79
	v_cvt_pk_bf16_f32 v37, v80, v81
	v_cvt_pk_bf16_f32 v38, v60, v61
	v_cvt_pk_bf16_f32 v39, v62, v63
	s_add_i32 s3, s3, s54
	s_waitcnt lgkmcnt(1)
	v_mfma_f32_32x32x16_bf16 v[4:19], v[44:47], v[36:39], v[4:19]
	v_add_f32_e32 v44, v68, v69
	v_add_f32_e32 v3, v44, v3
	v_add_f32_e32 v44, v64, v65
	v_add_f32_e32 v3, v44, v3
	v_add_f32_e32 v44, v66, v67
	v_add_f32_e32 v3, v44, v3
	ds_read_b128 v[44:47], v146 offset:17952
	s_waitcnt lgkmcnt(1)
	v_mfma_f32_32x32x16_bf16 v[20:35], v[48:51], v[52:55], v[20:35]
	v_add_f32_e32 v48, v70, v71
	v_add_f32_e32 v3, v48, v3
	v_add_f32_e32 v48, v72, v73
	v_add_f32_e32 v3, v48, v3
	v_add_f32_e32 v48, v74, v75
	v_add_f32_e32 v3, v48, v3
	ds_read_b128 v[48:51], v146 offset:17984
	s_waitcnt lgkmcnt(1)
	v_mfma_f32_32x32x16_bf16 v[20:35], v[44:47], v[56:59], v[20:35]
	v_add_f32_e32 v44, v76, v77
	v_add_f32_e32 v3, v44, v3
	v_add_f32_e32 v52, v78, v79
	v_add_f32_e32 v53, v80, v81
	v_add_f32_e32 v3, v52, v3
	v_add_f32_e32 v54, v60, v61
	v_add_f32_e32 v3, v53, v3
	v_add_f32_e32 v55, v62, v63
	v_add_f32_e32 v3, v54, v3
	v_add_f32_e32 v3, v55, v3
	v_add_f32_e32 v3, v127, v3
	ds_read_b128 v[44:47], v146 offset:18016
	s_waitcnt lgkmcnt(1)
	v_mfma_f32_32x32x16_bf16 v[20:35], v[48:51], v[40:43], v[20:35]
	ds_bpermute_b32 v40, v125, v3
	v_mov_b32_e32 v127, v2
	s_cmpk_gt_i32 s3, 0x3ff
	s_waitcnt lgkmcnt(0)
	v_add_f32_e32 v3, v3, v40
	v_div_scale_f32 v40, s[12:13], v3, v3, 1.0
	v_rcp_f32_e32 v41, v40
	v_mfma_f32_32x32x16_bf16 v[20:35], v[44:47], v[36:39], v[20:35]
	v_fma_f32 v36, -v40, v41, 1.0
	v_fmac_f32_e32 v41, v36, v41
	v_div_scale_f32 v36, vcc, 1.0, v3, 1.0
	v_mul_f32_e32 v37, v36, v41
	v_fma_f32 v38, -v40, v37, v36
	v_fmac_f32_e32 v37, v38, v41
	v_fma_f32 v36, -v40, v37, v36
	v_div_fmas_f32 v36, v36, v41, v37
	v_div_fixup_f32 v3, v36, v3, 1.0
	v_lshlrev_b64 v[36:37], 11, v[128:129]
	v_lshl_add_u64 v[36:37], s[10:11], 0, v[36:37]
	v_mul_f32_e32 v4, v4, v3
	v_mul_f32_e32 v5, v5, v3
	v_lshl_add_u64 v[36:37], v[36:37], 0, s[16:17]
	v_cvt_pk_bf16_f32 v4, v4, v5
	v_mul_f32_e32 v5, v6, v3
	v_mul_f32_e32 v6, v7, v3
	v_cvt_pk_bf16_f32 v5, v5, v6
	v_lshl_add_u64 v[6:7], v[36:37], 0, v[126:127]
	global_store_dwordx2 v[6:7], v[4:5], off
	v_mul_f32_e32 v4, v8, v3
	v_mul_f32_e32 v5, v9, v3
	v_cvt_pk_bf16_f32 v4, v4, v5
	v_mul_f32_e32 v5, v10, v3
	v_mul_f32_e32 v8, v11, v3
	v_cvt_pk_bf16_f32 v5, v5, v8
	global_store_dwordx2 v[6:7], v[4:5], off offset:16
	v_mul_f32_e32 v4, v12, v3
	v_mul_f32_e32 v5, v13, v3
	v_cvt_pk_bf16_f32 v4, v4, v5
	v_mul_f32_e32 v5, v14, v3
	v_mul_f32_e32 v8, v15, v3
	v_cvt_pk_bf16_f32 v5, v5, v8
	global_store_dwordx2 v[6:7], v[4:5], off offset:32
	v_mul_f32_e32 v4, v16, v3
	v_mul_f32_e32 v5, v17, v3
	v_cvt_pk_bf16_f32 v4, v4, v5
	v_mul_f32_e32 v5, v18, v3
	v_mul_f32_e32 v8, v19, v3
	v_cvt_pk_bf16_f32 v5, v5, v8
	global_store_dwordx2 v[6:7], v[4:5], off offset:48
	v_mul_f32_e32 v4, v20, v3
	v_mul_f32_e32 v5, v21, v3
	v_cvt_pk_bf16_f32 v4, v4, v5
	v_mul_f32_e32 v5, v22, v3
	v_mul_f32_e32 v8, v23, v3
	v_cvt_pk_bf16_f32 v5, v5, v8
	global_store_dwordx2 v[6:7], v[4:5], off offset:64
	v_mul_f32_e32 v4, v24, v3
	v_mul_f32_e32 v5, v25, v3
	v_cvt_pk_bf16_f32 v4, v4, v5
	v_mul_f32_e32 v5, v26, v3
	v_mul_f32_e32 v8, v27, v3
	v_cvt_pk_bf16_f32 v5, v5, v8
	global_store_dwordx2 v[6:7], v[4:5], off offset:80
	v_mul_f32_e32 v4, v28, v3
	v_mul_f32_e32 v5, v29, v3
	v_cvt_pk_bf16_f32 v4, v4, v5
	v_mul_f32_e32 v5, v30, v3
	v_mul_f32_e32 v8, v31, v3
	v_cvt_pk_bf16_f32 v5, v5, v8
	global_store_dwordx2 v[6:7], v[4:5], off offset:96
	v_mul_f32_e32 v4, v32, v3
	v_mul_f32_e32 v5, v33, v3
	v_cvt_pk_bf16_f32 v4, v4, v5
	v_mul_f32_e32 v5, v34, v3
	v_mul_f32_e32 v3, v35, v3
	v_cvt_pk_bf16_f32 v5, v5, v3
	global_store_dwordx2 v[6:7], v[4:5], off offset:112
	v_xor_b32_e32 v146, 0x8000, v146
	s_cbranch_scc1 .LBB0_2039

; #define ATT_GLOAD(kt) do { \
;       rk0 = *(const uint4*)(kn_base + (size_t)((kt) * 64 + srow) * 1024 + sch * 8); \
;       rv0 = *(const uint4*)(vt_base + (size_t)srow * 2304 + (kt) * 64 + sch * 8); \
;       if (tid < 256) rp = *(const uint4*)(kpe_base + (size_t)((kt) * 64 + (tid >> 2)) * 32 + (tid & 3) * 8); } while (0)
; __device__ __forceinline__ void phase_attn(CP& p, char* smem, int vid0, int grid) {
;     ...
;     ATT_GLOAD(0);
;     for (int kt = 0; kt < 36; ++kt) {
;       __syncthreads();
;       {
;         *(uint4*)(Ks + srow * 104 + sch * 8) = rk0;
;         uint2 lo, hi;
;         lo.x = rv0.x; lo.y = rv0.y; hi.x = rv0.z; hi.y = rv0.w;
;         *(uint2*)(Vs + srow * 72 + (sch >> 1) * 16 + (sch & 1) * 4) = lo; *(uint2*)(Vs + srow * 72 + (sch >> 1) * 16 + 8 + (sch & 1) * 4) = hi;
;       }
;       if (tid < 256) *(uint4*)(Ks + (tid >> 2) * 104 + 64 + (tid & 3) * 8) = rp;
;       __syncthreads();
;       if (kt + 1 < 36) ATT_GLOAD(kt + 1);
;       f32x16 s[2];
; #pragma unroll
;       for (int t2 = 0; t2 < 2; ++t2) {
; #pragma unroll
;         for (int i = 0; i < 16; ++i) s[t2][i] = 0.f;
; #pragma unroll
;         for (int kk = 0; kk < 6; ++kk) {
;           const bf16x8 a = *(const bf16x8*)(Ks + (32 * t2 + r) * 104 + 16 * kk + 8 * hh);
;           s[t2] = __builtin_amdgcn_mfma_f32_32x32x16_bf16(a, qf[kk], s[t2], 0, 0, 0);
;         }
;       }
;       float mx = s[0][0];
; #pragma unroll
;       for (int i = 1; i < 16; ++i) mx = fmaxf(mx, s[0][i]);
; #pragma unroll
;       for (int i = 0; i < 16; ++i) mx = fmaxf(mx, s[1][i]);
;       mx = fmaxf(mx, __shfl_xor(mx, 32));
;       const float mcand = mx * cs;
;       if (__builtin_amdgcn_ballot_w64(mcand > mrun + 6.0f) != 0ull) {
;         const float mnew_ = fmaxf(mrun, mcand);
;         const float alpha = __builtin_amdgcn_exp2f(mrun - mnew_);
;         mrun = mnew_;
;         lrun *= alpha;
; #pragma unroll
;         for (int i = 0; i < 16; ++i) { oacc[0][i] *= alpha; oacc[1][i] *= alpha; }
;       }
.Lattn_p0:
	v_add_u32_e32 v3, 0x3000, v139
	s_barrier
	s_waitcnt vmcnt(1)
	ds_write_b128 v138, v[96:99]
	s_waitcnt vmcnt(0)
	ds_write2_b64 v3, v[92:93], v[94:95] offset0:128 offset1:130
	s_and_saveexec_b64 s[22:23], s[6:7]
	ds_write_b128 v140, v[100:103] offset:128
	s_or_b64 exec, exec, s[22:23]
	s_waitcnt lgkmcnt(0)
	s_barrier
	global_load_dwordx4 v[96:99], v[134:135], off
	global_load_dwordx4 v[92:95], v[132:133], off
	s_and_saveexec_b64 s[22:23], s[6:7]
	s_cbranch_execz .Lattn_nokpe_P
	v_lshl_add_u64 v[204:205], v[130:131], 0, s[12:13]
	v_add_co_u32_e32 v204, vcc, 0x1000, v204
	s_nop 1
	v_addc_co_u32_e32 v205, vcc, 0, v205, vcc
	global_load_dwordx4 v[100:103], v[204:205], off
.Lattn_nokpe_P:
	s_or_b64 exec, exec, s[22:23]
	s_add_u32 s12, s12, 0x1000
	s_addc_u32 s13, s13, 0
	v_lshl_add_u64 v[132:133], v[132:133], 0, s[18:19]
	v_lshl_add_u64 v[134:135], v[134:135], 0, s[20:21]
	ds_read_b128 v[204:207], v145
	ds_read_b128 v[208:211], v145 offset:32
	ds_read_b128 v[212:215], v145 offset:64
	ds_read_b128 v[216:219], v145 offset:96
	ds_read_b128 v[220:223], v145 offset:128
	ds_read_b128 v[224:227], v145 offset:160
	ds_read_b128 v[228:231], v145 offset:6656
	ds_read_b128 v[232:235], v145 offset:6688
	ds_read_b128 v[236:239], v145 offset:6720
	ds_read_b128 v[240:243], v145 offset:6752
	ds_read_b128 v[244:247], v145 offset:6784
	ds_read_b128 v[252:255], v145 offset:6816
	s_waitcnt lgkmcnt(11)
	v_mfma_f32_32x32x16_bf16 v[188:203], v[204:207], v[72:75], 0
	s_waitcnt lgkmcnt(10)
	v_mfma_f32_32x32x16_bf16 v[188:203], v[208:211], v[68:71], v[188:203]
	s_waitcnt lgkmcnt(9)
	v_mfma_f32_32x32x16_bf16 v[188:203], v[212:215], v[80:83], v[188:203]
	s_waitcnt lgkmcnt(8)
	v_mfma_f32_32x32x16_bf16 v[188:203], v[216:219], v[76:79], v[188:203]
	s_waitcnt lgkmcnt(7)
	v_mfma_f32_32x32x16_bf16 v[188:203], v[220:223], v[84:87], v[188:203]
	s_waitcnt lgkmcnt(6)
	v_mfma_f32_32x32x16_bf16 v[188:203], v[224:227], v[88:91], v[188:203]
	s_waitcnt lgkmcnt(5)
	v_mfma_f32_32x32x16_bf16 v[172:187], v[228:231], v[72:75], 0
	s_waitcnt lgkmcnt(4)
	v_mfma_f32_32x32x16_bf16 v[172:187], v[232:235], v[68:71], v[172:187]
	s_waitcnt lgkmcnt(3)
	v_mfma_f32_32x32x16_bf16 v[172:187], v[236:239], v[80:83], v[172:187]
	s_waitcnt lgkmcnt(2)
	v_mfma_f32_32x32x16_bf16 v[172:187], v[240:243], v[76:79], v[172:187]
	s_waitcnt lgkmcnt(1)
	v_mfma_f32_32x32x16_bf16 v[172:187], v[244:247], v[84:87], v[172:187]
	s_waitcnt lgkmcnt(0)
	v_mfma_f32_32x32x16_bf16 v[172:187], v[252:255], v[88:91], v[172:187]
	s_nop 7
	s_nop 3
	v_max_f32_e32 v156, v189, v189
	v_max_f32_e32 v157, v188, v188
	v_max_f32_e32 v156, v157, v156
	v_max3_f32 v148, v156, v190, v191
	v_max3_f32 v148, v148, v192, v193
	v_max3_f32 v148, v148, v194, v195
	v_max3_f32 v148, v148, v196, v197
	v_max3_f32 v148, v148, v198, v199
	v_max3_f32 v148, v148, v200, v201
	v_max3_f32 v148, v148, v202, v203
	v_max3_f32 v148, v148, v172, v173
	v_max3_f32 v148, v148, v174, v175
	v_max3_f32 v148, v148, v176, v177
	v_max3_f32 v148, v148, v178, v179
	v_max3_f32 v148, v148, v180, v181
	v_max3_f32 v148, v148, v182, v183
	v_max3_f32 v148, v148, v184, v185
	v_max3_f32 v148, v148, v186, v187
	ds_bpermute_b32 v149, v125, v148
	s_waitcnt lgkmcnt(0)
	v_max_f32_e32 v149, v149, v149
	v_max_f32_e32 v148, v148, v149
	v_mul_f32_e32 v148, 0x3e16c740, v148
	v_add_f32_e32 v149, 0x40c00000, v147
	v_cmp_gt_f32_e32 vcc, v148, v149
	s_cbranch_vccz .Lattn_norescale_P
	v_max_f32_e32 v148, v148, v148
	v_max_f32_e32 v149, v147, v147
	v_max_f32_e32 v149, v149, v148
	v_sub_f32_e32 v147, v147, v149
	v_exp_f32_e32 v148, v147
	v_mov_b32_e32 v147, v149
	v_pk_mul_f32 v[34:35], v[34:35], v[148:149] op_sel_hi:[1,0]
	v_pk_mul_f32 v[32:33], v[32:33], v[148:149] op_sel_hi:[1,0]
	v_pk_mul_f32 v[30:31], v[30:31], v[148:149] op_sel_hi:[1,0]
	v_pk_mul_f32 v[28:29], v[28:29], v[148:149] op_sel_hi:[1,0]
	v_pk_mul_f32 v[26:27], v[26:27], v[148:149] op_sel_hi:[1,0]
	v_pk_mul_f32 v[24:25], v[24:25], v[148:149] op_sel_hi:[1,0]
	v_pk_mul_f32 v[22:23], v[22:23], v[148:149] op_sel_hi:[1,0]
	v_pk_mul_f32 v[20:21], v[20:21], v[148:149] op_sel_hi:[1,0]
	v_pk_mul_f32 v[18:19], v[18:19], v[148:149] op_sel_hi:[1,0]
	v_pk_mul_f32 v[16:17], v[16:17], v[148:149] op_sel_hi:[1,0]
	v_pk_mul_f32 v[14:15], v[14:15], v[148:149] op_sel_hi:[1,0]
	v_pk_mul_f32 v[12:13], v[12:13], v[148:149] op_sel_hi:[1,0]
	v_pk_mul_f32 v[10:11], v[10:11], v[148:149] op_sel_hi:[1,0]
	v_pk_mul_f32 v[8:9], v[8:9], v[148:149] op_sel_hi:[1,0]
	v_pk_mul_f32 v[6:7], v[6:7], v[148:149] op_sel_hi:[1,0]
	v_pk_mul_f32 v[4:5], v[4:5], v[148:149] op_sel_hi:[1,0]
	v_mul_f32_e32 v127, v127, v148
.Lattn_norescale_P:
	v_xor_b32_e32 v138, 0x8000, v138
	v_xor_b32_e32 v139, 0x8000, v139
	v_xor_b32_e32 v140, 0x8000, v140
	v_xor_b32_e32 v145, 0x8000, v145
.Lattn_body_B:
	v_add_u32_e32 v3, 0x3000, v139
	s_waitcnt vmcnt(1)
	ds_write_b128 v138, v[96:99]
	s_waitcnt vmcnt(0)
	s_and_saveexec_b64 s[22:23], s[6:7]
	ds_write_b128 v140, v[100:103] offset:128
	s_or_b64 exec, exec, s[22:23]
	s_waitcnt lgkmcnt(0)
	s_barrier
	ds_write2_b64 v3, v[92:93], v[94:95] offset0:128 offset1:130
	s_cmp_eq_u32 s12, 0x23000
	s_cbranch_scc1 .Lattn_nogl_B
	global_load_dwordx4 v[96:99], v[134:135], off
	global_load_dwordx4 v[92:95], v[132:133], off
	s_and_saveexec_b64 s[22:23], s[6:7]
	s_cbranch_execz .Lattn_nokpe_B
	v_lshl_add_u64 v[204:205], v[130:131], 0, s[12:13]
	v_add_co_u32_e32 v204, vcc, 0x1000, v204
	s_nop 1
	v_addc_co_u32_e32 v205, vcc, 0, v205, vcc
	global_load_dwordx4 v[100:103], v[204:205], off

; __device__ __forceinline__ unsigned pack2(float a, float b) { unsigned r; asm("v_cvt_pk_bf16_f32 %0, %1, %2" : "=v"(r) : "v"(a), "v"(b)); return r; }
; __device__ __forceinline__ void phase_attn(CP& p, char* smem, int vid0, int grid) {
;     ...
;       f32x16 s[2];
; #pragma unroll
;       for (int t2 = 0; t2 < 2; ++t2) {
; #pragma unroll
;         for (int i = 0; i < 16; ++i) s[t2][i] = 0.f;
; #pragma unroll
;         for (int kk = 0; kk < 6; ++kk) {
;           const bf16x8 a = *(const bf16x8*)(Ks + (32 * t2 + r) * 104 + 16 * kk + 8 * hh);
;           s[t2] = __builtin_amdgcn_mfma_f32_32x32x16_bf16(a, qf[kk], s[t2], 0, 0, 0);
;         }
;       }
;       float mx = s[0][0];
; #pragma unroll
;       for (int i = 1; i < 16; ++i) mx = fmaxf(mx, s[0][i]);
; #pragma unroll
;       for (int i = 0; i < 16; ++i) mx = fmaxf(mx, s[1][i]);
;       mx = fmaxf(mx, __shfl_xor(mx, 32));
;       const float mcand = mx * cs;
;       if (__builtin_amdgcn_ballot_w64(mcand > mrun + 6.0f) != 0ull) {
;         const float mnew_ = fmaxf(mrun, mcand);
;         const float alpha = __builtin_amdgcn_exp2f(mrun - mnew_);
;         mrun = mnew_;
;         lrun *= alpha;
; #pragma unroll
;         for (int i = 0; i < 16; ++i) { oacc[0][i] *= alpha; oacc[1][i] *= alpha; }
;       }
;       const float mnew = mrun;
;       float psum = 0.f;
;       bf16x8 pf[4];
; #pragma unroll
;       for (int t2 = 0; t2 < 2; ++t2)
; #pragma unroll
;         for (int hf = 0; hf < 2; ++hf) {
;           union { unsigned u[4]; bf16x8 v; } cvp;
; #pragma unroll
;           for (int i = 0; i < 4; ++i) {
;             const float p0 = __builtin_amdgcn_exp2f(s[t2][hf * 8 + 2 * i] * cs - mnew);
;             const float p1 = __builtin_amdgcn_exp2f(s[t2][hf * 8 + 2 * i + 1] * cs - mnew);
;             psum += p0 + p1;
;             cvp.u[i] = pack2(p0, p1);
;           }
;           pf[t2 * 2 + hf] = cvp.v;
;         }
;       lrun += psum;
; #pragma unroll
;       for (int dt = 0; dt < 2; ++dt)
; #pragma unroll
;         for (int s4 = 0; s4 < 4; ++s4) {
;           const bf16x8 vfr = *(const bf16x8*)(Vs + (32 * dt + r) * 72 + 16 * s4 + 8 * hh);
;           oacc[dt] = __builtin_amdgcn_mfma_f32_32x32x16_bf16(vfr, pf[s4], oacc[dt], 0, 0, 0);
;         }
.Lattn_nogl_B:
	ds_read_b128 v[204:207], v145
	ds_read_b128 v[208:211], v145 offset:32
	ds_read_b128 v[212:215], v145 offset:64
	ds_read_b128 v[216:219], v145 offset:96
	ds_read_b128 v[220:223], v145 offset:128
	ds_read_b128 v[224:227], v145 offset:160
	ds_read_b128 v[228:231], v145 offset:6656
	ds_read_b128 v[232:235], v145 offset:6688
	ds_read_b128 v[236:239], v145 offset:6720
	ds_read_b128 v[240:243], v145 offset:6752
	ds_read_b128 v[244:247], v145 offset:6784
	ds_read_b128 v[252:255], v145 offset:6816
	v_fma_f32 v188, v188, s25, -v147
	v_exp_f32_e32 v164, v188
	v_fma_f32 v188, v189, s25, -v147
	v_exp_f32_e32 v165, v188
	v_fma_f32 v188, v190, s25, -v147
	v_exp_f32_e32 v166, v188
	s_waitcnt lgkmcnt(11)
	v_mfma_f32_32x32x16_bf16 v[52:67], v[204:207], v[72:75], 0
	v_fma_f32 v188, v191, s25, -v147
	v_exp_f32_e32 v167, v188
	v_fma_f32 v188, v192, s25, -v147
	v_fma_f32 v192, v196, s25, -v147
	v_exp_f32_e32 v149, v192
	v_fma_f32 v192, v197, s25, -v147
	s_waitcnt lgkmcnt(10)
	v_mfma_f32_32x32x16_bf16 v[52:67], v[208:211], v[68:71], v[52:67]
	v_exp_f32_e32 v151, v192
	v_fma_f32 v192, v198, s25, -v147
	v_exp_f32_e32 v148, v192
	v_fma_f32 v192, v199, s25, -v147
	v_exp_f32_e32 v150, v192
	v_fma_f32 v192, v200, s25, -v147
	s_waitcnt lgkmcnt(9)
	v_mfma_f32_32x32x16_bf16 v[52:67], v[212:215], v[80:83], v[52:67]
	v_exp_f32_e32 v153, v192
	v_fma_f32 v192, v201, s25, -v147
	v_exp_f32_e32 v201, v192
	v_fma_f32 v192, v202, s25, -v147
	v_fma_f32 v172, v172, s25, -v147
	v_exp_f32_e32 v152, v192
	s_waitcnt lgkmcnt(8)
	v_mfma_f32_32x32x16_bf16 v[52:67], v[216:219], v[76:79], v[52:67]
	v_fma_f32 v192, v203, s25, -v147
	v_exp_f32_e32 v203, v172
	v_fma_f32 v172, v173, s25, -v147
	v_exp_f32_e32 v155, v172
	v_fma_f32 v172, v174, s25, -v147
	v_exp_f32_e32 v202, v172
	s_waitcnt lgkmcnt(7)
	v_mfma_f32_32x32x16_bf16 v[52:67], v[220:223], v[84:87], v[52:67]
	v_fma_f32 v172, v175, s25, -v147
	v_exp_f32_e32 v154, v172
	v_fma_f32 v172, v176, s25, -v147
	v_exp_f32_e32 v157, v172
	v_fma_f32 v172, v177, s25, -v147
	v_exp_f32_e32 v159, v172
	s_waitcnt lgkmcnt(6)
	v_mfma_f32_32x32x16_bf16 v[52:67], v[224:227], v[88:91], v[52:67]
	v_fma_f32 v172, v178, s25, -v147
	v_exp_f32_e32 v156, v172
	s_waitcnt lgkmcnt(0)
	ds_read_b128 v[172:175], v146 offset:13312
	ds_read_b128 v[196:199], v146 offset:13344
	v_exp_f32_e32 v168, v188
	v_fma_f32 v188, v193, s25, -v147
	v_exp_f32_e32 v169, v188
	v_fma_f32 v188, v194, s25, -v147
	v_mfma_f32_32x32x16_bf16 v[36:51], v[228:231], v[72:75], 0
	v_exp_f32_e32 v170, v188
	v_fma_f32 v188, v195, s25, -v147
	v_exp_f32_e32 v171, v188
	v_cvt_pk_bf16_f32 v188, v164, v165
	v_cvt_pk_bf16_f32 v189, v166, v167
	v_cvt_pk_bf16_f32 v190, v168, v169
	v_cvt_pk_bf16_f32 v191, v170, v171
	v_exp_f32_e32 v200, v192
	s_waitcnt lgkmcnt(1)
	v_mfma_f32_32x32x16_bf16 v[4:19], v[172:175], v[188:191], v[4:19]
	v_fma_f32 v172, v181, s25, -v147
	v_exp_f32_e32 v163, v172
	v_fma_f32 v172, v182, s25, -v147
	v_exp_f32_e32 v160, v172
	v_mfma_f32_32x32x16_bf16 v[36:51], v[232:235], v[68:71], v[36:51]
	ds_read_b128 v[172:175], v146 offset:13376
	v_cvt_pk_bf16_f32 v192, v149, v151
	v_cvt_pk_bf16_f32 v193, v148, v150
	v_cvt_pk_bf16_f32 v194, v153, v201
	v_cvt_pk_bf16_f32 v195, v152, v200
	v_fma_f32 v180, v180, s25, -v147
	s_waitcnt lgkmcnt(1)
	v_mfma_f32_32x32x16_bf16 v[4:19], v[196:199], v[192:195], v[4:19]
	v_exp_f32_e32 v161, v180
	v_fma_f32 v180, v183, s25, -v147
	v_exp_f32_e32 v162, v180
	v_fma_f32 v180, v184, s25, -v147
	v_exp_f32_e32 v197, v180
	v_fma_f32 v180, v185, s25, -v147
	v_mfma_f32_32x32x16_bf16 v[36:51], v[236:239], v[80:83], v[36:51]
	v_fma_f32 v176, v179, s25, -v147
	v_exp_f32_e32 v199, v180
	ds_read_b128 v[180:183], v146 offset:13408
	v_exp_f32_e32 v158, v176
	v_cvt_pk_bf16_f32 v176, v203, v155
	v_cvt_pk_bf16_f32 v177, v202, v154
	v_cvt_pk_bf16_f32 v178, v157, v159
	v_cvt_pk_bf16_f32 v179, v156, v158
	v_fma_f32 v184, v186, s25, -v147
	s_waitcnt lgkmcnt(1)
	v_mfma_f32_32x32x16_bf16 v[4:19], v[172:175], v[176:179], v[4:19]
	v_fma_f32 v172, v187, s25, -v147
	v_exp_f32_e32 v196, v184
	v_exp_f32_e32 v198, v172
	v_mfma_f32_32x32x16_bf16 v[36:51], v[240:243], v[76:79], v[36:51]
	v_cvt_pk_bf16_f32 v172, v161, v163
	v_cvt_pk_bf16_f32 v173, v160, v162
	v_cvt_pk_bf16_f32 v174, v197, v199
	v_cvt_pk_bf16_f32 v175, v196, v198
	v_add_f32_e32 v184, v164, v165
	s_waitcnt lgkmcnt(0)
; __device__ __forceinline__ unsigned pack2(float a, float b) { unsigned r; asm("v_cvt_pk_bf16_f32 %0, %1, %2" : "=v"(r) : "v"(a), "v"(b)); return r; }
; __device__ __forceinline__ void phase_attn(CP& p, char* smem, int vid0, int grid) {
;     ...
;       float mx = s[0][0];
; #pragma unroll
;       for (int i = 1; i < 16; ++i) mx = fmaxf(mx, s[0][i]);
; #pragma unroll
;       for (int i = 0; i < 16; ++i) mx = fmaxf(mx, s[1][i]);
;       mx = fmaxf(mx, __shfl_xor(mx, 32));
;       const float mcand = mx * cs;
;       if (__builtin_amdgcn_ballot_w64(mcand > mrun + 6.0f) != 0ull) {
;         const float mnew_ = fmaxf(mrun, mcand);
;         const float alpha = __builtin_amdgcn_exp2f(mrun - mnew_);
;         mrun = mnew_;
;         lrun *= alpha;
; #pragma unroll
;         for (int i = 0; i < 16; ++i) { oacc[0][i] *= alpha; oacc[1][i] *= alpha; }
;       }
;       const float mnew = mrun;
;       float psum = 0.f;
;       bf16x8 pf[4];
; #pragma unroll
;       for (int t2 = 0; t2 < 2; ++t2)
; #pragma unroll
;         for (int hf = 0; hf < 2; ++hf) {
;           union { unsigned u[4]; bf16x8 v; } cvp;
; #pragma unroll
;           for (int i = 0; i < 4; ++i) {
;             const float p0 = __builtin_amdgcn_exp2f(s[t2][hf * 8 + 2 * i] * cs - mnew);
;             const float p1 = __builtin_amdgcn_exp2f(s[t2][hf * 8 + 2 * i + 1] * cs - mnew);
;             psum += p0 + p1;
;             cvp.u[i] = pack2(p0, p1);
;           }
;           pf[t2 * 2 + hf] = cvp.v;
;         }
;       lrun += psum;
; #pragma unroll
;       for (int dt = 0; dt < 2; ++dt)
; #pragma unroll
;         for (int s4 = 0; s4 < 4; ++s4) {
;           const bf16x8 vfr = *(const bf16x8*)(Vs + (32 * dt + r) * 72 + 16 * s4 + 8 * hh);
;           oacc[dt] = __builtin_amdgcn_mfma_f32_32x32x16_bf16(vfr, pf[s4], oacc[dt], 0, 0, 0);
;         }
	v_mfma_f32_32x32x16_bf16 v[4:19], v[180:183], v[172:175], v[4:19]
	ds_read_b128 v[180:183], v146 offset:17920
	v_add_f32_e32 v164, 0, v184
	ds_read_b128 v[184:187], v146 offset:17952
	v_add_f32_e32 v165, v166, v167
	s_add_u32 s12, s12, 0x1000
	s_addc_u32 s13, s13, 0
	v_lshl_add_u64 v[132:133], v[132:133], 0, s[18:19]
	s_waitcnt lgkmcnt(1)
	v_mfma_f32_32x32x16_bf16 v[20:35], v[180:183], v[188:191], v[20:35]
	v_add_f32_e32 v180, v165, v164
	v_add_f32_e32 v181, v168, v169
	v_mfma_f32_32x32x16_bf16 v[36:51], v[244:247], v[84:87], v[36:51]
	v_add_f32_e32 v180, v181, v180
	v_add_f32_e32 v181, v170, v171
	v_add_f32_e32 v190, v181, v180
	ds_read_b128 v[180:183], v146 offset:17984
	v_pk_add_f32 v[188:189], v[148:149], v[150:151]
	s_waitcnt lgkmcnt(1)
	v_mfma_f32_32x32x16_bf16 v[20:35], v[184:187], v[192:195], v[20:35]
	v_add_f32_e32 v184, v189, v190
	v_add_f32_e32 v186, v188, v184
	v_add_f32_e64 v184, v152, v200
	v_add_f32_e64 v185, v153, v201
	v_add_f32_e64 v188, v202, v154
	v_mfma_f32_32x32x16_bf16 v[36:51], v[252:255], v[88:91], v[36:51]
	v_add_f32_e64 v189, v203, v155
	v_add_f32_e32 v185, v185, v186
	v_add_f32_e32 v190, v184, v185
	ds_read_b128 v[184:187], v146 offset:18016
	s_waitcnt lgkmcnt(1)
	v_mfma_f32_32x32x16_bf16 v[20:35], v[180:183], v[176:179], v[20:35]
	v_add_f32_e32 v176, v189, v190
	v_add_f32_e32 v178, v188, v176
	v_add_f32_e64 v176, v156, v158
	v_add_f32_e64 v177, v157, v159
	v_add_f32_e32 v177, v177, v178
	v_add_f32_e32 v180, v176, v177
	v_pk_add_f32 v[176:177], v[160:161], v[162:163]
	s_waitcnt lgkmcnt(0)
	v_mfma_f32_32x32x16_bf16 v[20:35], v[184:187], v[172:175], v[20:35]
	v_add_f32_e32 v172, v177, v180
	v_add_f32_e64 v178, v196, v198
	v_add_f32_e64 v179, v197, v199
	v_add_f32_e32 v172, v176, v172
	v_add_f32_e32 v172, v179, v172
	v_add_f32_e32 v172, v178, v172
	v_add_f32_e32 v127, v127, v172
	v_lshl_add_u64 v[134:135], v[134:135], 0, s[20:21]
	v_max_f32_e32 v156, v53, v53
	v_max_f32_e32 v157, v52, v52
	v_max_f32_e32 v156, v157, v156
	v_max3_f32 v148, v156, v54, v55
	v_max3_f32 v148, v148, v56, v57
	v_max3_f32 v148, v148, v58, v59
	v_max3_f32 v148, v148, v60, v61
	v_max3_f32 v148, v148, v62, v63
	v_max3_f32 v148, v148, v64, v65
	v_max3_f32 v148, v148, v66, v67
	v_max3_f32 v148, v148, v36, v37
	v_max3_f32 v148, v148, v38, v39
	v_max3_f32 v148, v148, v40, v41
	v_max3_f32 v148, v148, v42, v43
	v_max3_f32 v148, v148, v44, v45
	v_max3_f32 v148, v148, v46, v47
	v_max3_f32 v148, v148, v48, v49
	v_max3_f32 v148, v148, v50, v51
	ds_bpermute_b32 v149, v125, v148
	s_waitcnt lgkmcnt(0)
	v_max_f32_e32 v149, v149, v149
	v_max_f32_e32 v148, v148, v149
	v_mul_f32_e32 v148, 0x3e16c740, v148
	v_add_f32_e32 v149, 0x40c00000, v147
	v_cmp_gt_f32_e32 vcc, v148, v149
	s_cbranch_vccz .Lattn_norescale_B
	v_max_f32_e32 v148, v148, v148
	v_max_f32_e32 v149, v147, v147
	v_max_f32_e32 v149, v149, v148
	v_sub_f32_e32 v147, v147, v149
	v_exp_f32_e32 v148, v147
	v_mov_b32_e32 v147, v149
	v_pk_mul_f32 v[34:35], v[34:35], v[148:149] op_sel_hi:[1,0]
	v_pk_mul_f32 v[32:33], v[32:33], v[148:149] op_sel_hi:[1,0]
	v_pk_mul_f32 v[30:31], v[30:31], v[148:149] op_sel_hi:[1,0]
	v_pk_mul_f32 v[28:29], v[28:29], v[148:149] op_sel_hi:[1,0]
	v_pk_mul_f32 v[26:27], v[26:27], v[148:149] op_sel_hi:[1,0]
	v_pk_mul_f32 v[24:25], v[24:25], v[148:149] op_sel_hi:[1,0]
	v_pk_mul_f32 v[22:23], v[22:23], v[148:149] op_sel_hi:[1,0]
	v_pk_mul_f32 v[20:21], v[20:21], v[148:149] op_sel_hi:[1,0]
	v_pk_mul_f32 v[18:19], v[18:19], v[148:149] op_sel_hi:[1,0]
	v_pk_mul_f32 v[16:17], v[16:17], v[148:149] op_sel_hi:[1,0]
	v_pk_mul_f32 v[14:15], v[14:15], v[148:149] op_sel_hi:[1,0]
	v_pk_mul_f32 v[12:13], v[12:13], v[148:149] op_sel_hi:[1,0]
	v_pk_mul_f32 v[10:11], v[10:11], v[148:149] op_sel_hi:[1,0]
	v_pk_mul_f32 v[8:9], v[8:9], v[148:149] op_sel_hi:[1,0]
	v_pk_mul_f32 v[6:7], v[6:7], v[148:149] op_sel_hi:[1,0]
	v_pk_mul_f32 v[4:5], v[4:5], v[148:149] op_sel_hi:[1,0]
	v_mul_f32_e32 v127, v127, v148
.Lattn_norescale_B:
	v_xor_b32_e32 v138, 0x8000, v138
	v_xor_b32_e32 v139, 0x8000, v139
	v_xor_b32_e32 v140, 0x8000, v140
	v_xor_b32_e32 v145, 0x8000, v145
	v_xor_b32_e32 v146, 0x8000, v146
	s_cmp_eq_u32 s12, 0x24000
	s_cbranch_scc1 .Lattn_tail

; __device__ __forceinline__ unsigned pack2(float a, float b) { unsigned r; asm("v_cvt_pk_bf16_f32 %0, %1, %2" : "=v"(r) : "v"(a), "v"(b)); return r; }
; __device__ __forceinline__ void phase_attn(CP& p, char* smem, int vid0, int grid) {
;     ...
;       f32x16 s[2];
; #pragma unroll
;       for (int t2 = 0; t2 < 2; ++t2) {
; #pragma unroll
;         for (int i = 0; i < 16; ++i) s[t2][i] = 0.f;
; #pragma unroll
;         for (int kk = 0; kk < 6; ++kk) {
;           const bf16x8 a = *(const bf16x8*)(Ks + (32 * t2 + r) * 104 + 16 * kk + 8 * hh);
;           s[t2] = __builtin_amdgcn_mfma_f32_32x32x16_bf16(a, qf[kk], s[t2], 0, 0, 0);
;         }
;       }
;       float mx = s[0][0];
; #pragma unroll
;       for (int i = 1; i < 16; ++i) mx = fmaxf(mx, s[0][i]);
; #pragma unroll
;       for (int i = 0; i < 16; ++i) mx = fmaxf(mx, s[1][i]);
;       mx = fmaxf(mx, __shfl_xor(mx, 32));
;       const float mcand = mx * cs;
;       if (__builtin_amdgcn_ballot_w64(mcand > mrun + 6.0f) != 0ull) {
;         const float mnew_ = fmaxf(mrun, mcand);
;         const float alpha = __builtin_amdgcn_exp2f(mrun - mnew_);
;         mrun = mnew_;
;         lrun *= alpha;
; #pragma unroll
;         for (int i = 0; i < 16; ++i) { oacc[0][i] *= alpha; oacc[1][i] *= alpha; }
;       }
;       const float mnew = mrun;
;       float psum = 0.f;
;       bf16x8 pf[4];
; #pragma unroll
;       for (int t2 = 0; t2 < 2; ++t2)
; #pragma unroll
;         for (int hf = 0; hf < 2; ++hf) {
;           union { unsigned u[4]; bf16x8 v; } cvp;
; #pragma unroll
;           for (int i = 0; i < 4; ++i) {
;             const float p0 = __builtin_amdgcn_exp2f(s[t2][hf * 8 + 2 * i] * cs - mnew);
;             const float p1 = __builtin_amdgcn_exp2f(s[t2][hf * 8 + 2 * i + 1] * cs - mnew);
;             psum += p0 + p1;
;             cvp.u[i] = pack2(p0, p1);
;           }
;           pf[t2 * 2 + hf] = cvp.v;
;         }
;       lrun += psum;
; #pragma unroll
;       for (int dt = 0; dt < 2; ++dt)
; #pragma unroll
;         for (int s4 = 0; s4 < 4; ++s4) {
;           const bf16x8 vfr = *(const bf16x8*)(Vs + (32 * dt + r) * 72 + 16 * s4 + 8 * hh);
;           oacc[dt] = __builtin_amdgcn_mfma_f32_32x32x16_bf16(vfr, pf[s4], oacc[dt], 0, 0, 0);
;         }
.Lattn_nogl_A:
	ds_read_b128 v[204:207], v145
	ds_read_b128 v[208:211], v145 offset:32
	ds_read_b128 v[212:215], v145 offset:64
	ds_read_b128 v[216:219], v145 offset:96
	ds_read_b128 v[220:223], v145 offset:128
	ds_read_b128 v[224:227], v145 offset:160
	ds_read_b128 v[228:231], v145 offset:6656
	ds_read_b128 v[232:235], v145 offset:6688
	ds_read_b128 v[236:239], v145 offset:6720
	ds_read_b128 v[240:243], v145 offset:6752
	ds_read_b128 v[244:247], v145 offset:6784
	ds_read_b128 v[252:255], v145 offset:6816
	v_fma_f32 v52, v52, s25, -v147
	v_exp_f32_e32 v164, v52
	v_fma_f32 v52, v53, s25, -v147
	v_exp_f32_e32 v165, v52
	v_fma_f32 v52, v54, s25, -v147
	v_exp_f32_e32 v166, v52
	s_waitcnt lgkmcnt(11)
	v_mfma_f32_32x32x16_bf16 v[188:203], v[204:207], v[72:75], 0
	v_fma_f32 v52, v55, s25, -v147
	v_exp_f32_e32 v167, v52
	v_fma_f32 v52, v56, s25, -v147
	v_fma_f32 v56, v60, s25, -v147
	v_exp_f32_e32 v149, v56
	v_fma_f32 v56, v61, s25, -v147
	s_waitcnt lgkmcnt(10)
	v_mfma_f32_32x32x16_bf16 v[188:203], v[208:211], v[68:71], v[188:203]
	v_exp_f32_e32 v151, v56
	v_fma_f32 v56, v62, s25, -v147
	v_exp_f32_e32 v148, v56
	v_fma_f32 v56, v63, s25, -v147
	v_exp_f32_e32 v150, v56
	v_fma_f32 v56, v64, s25, -v147
	s_waitcnt lgkmcnt(9)
	v_mfma_f32_32x32x16_bf16 v[188:203], v[212:215], v[80:83], v[188:203]
	v_exp_f32_e32 v153, v56
	v_fma_f32 v56, v65, s25, -v147
	v_exp_f32_e32 v65, v56
	v_fma_f32 v56, v66, s25, -v147
	v_fma_f32 v36, v36, s25, -v147
	v_exp_f32_e32 v152, v56
	s_waitcnt lgkmcnt(8)
	v_mfma_f32_32x32x16_bf16 v[188:203], v[216:219], v[76:79], v[188:203]
	v_fma_f32 v56, v67, s25, -v147
	v_exp_f32_e32 v67, v36
	v_fma_f32 v36, v37, s25, -v147
	v_exp_f32_e32 v155, v36
	v_fma_f32 v36, v38, s25, -v147
	v_exp_f32_e32 v66, v36
	s_waitcnt lgkmcnt(7)
	v_mfma_f32_32x32x16_bf16 v[188:203], v[220:223], v[84:87], v[188:203]
	v_fma_f32 v36, v39, s25, -v147
	v_exp_f32_e32 v154, v36
	v_fma_f32 v36, v40, s25, -v147
	v_exp_f32_e32 v157, v36
	v_fma_f32 v36, v41, s25, -v147
	v_exp_f32_e32 v159, v36
	s_waitcnt lgkmcnt(6)
	v_mfma_f32_32x32x16_bf16 v[188:203], v[224:227], v[88:91], v[188:203]
	v_fma_f32 v36, v42, s25, -v147
	v_exp_f32_e32 v156, v36
	s_waitcnt lgkmcnt(0)
	ds_read_b128 v[36:39], v146 offset:13312
	ds_read_b128 v[60:63], v146 offset:13344
	v_exp_f32_e32 v168, v52
	v_fma_f32 v52, v57, s25, -v147
	v_exp_f32_e32 v169, v52
	v_fma_f32 v52, v58, s25, -v147
	v_mfma_f32_32x32x16_bf16 v[172:187], v[228:231], v[72:75], 0
	v_exp_f32_e32 v170, v52
	v_fma_f32 v52, v59, s25, -v147
	v_exp_f32_e32 v171, v52
	v_cvt_pk_bf16_f32 v52, v164, v165
	v_cvt_pk_bf16_f32 v53, v166, v167
	v_cvt_pk_bf16_f32 v54, v168, v169
	v_cvt_pk_bf16_f32 v55, v170, v171
	v_exp_f32_e32 v64, v56
	s_waitcnt lgkmcnt(1)
	v_mfma_f32_32x32x16_bf16 v[4:19], v[36:39], v[52:55], v[4:19]
	v_fma_f32 v36, v45, s25, -v147
	v_exp_f32_e32 v163, v36
	v_fma_f32 v36, v46, s25, -v147
	v_exp_f32_e32 v160, v36
	v_mfma_f32_32x32x16_bf16 v[172:187], v[232:235], v[68:71], v[172:187]
	ds_read_b128 v[36:39], v146 offset:13376
	v_cvt_pk_bf16_f32 v56, v149, v151
	v_cvt_pk_bf16_f32 v57, v148, v150
	v_cvt_pk_bf16_f32 v58, v153, v65
	v_cvt_pk_bf16_f32 v59, v152, v64
	v_fma_f32 v44, v44, s25, -v147
	s_waitcnt lgkmcnt(1)
	v_mfma_f32_32x32x16_bf16 v[4:19], v[60:63], v[56:59], v[4:19]
	v_exp_f32_e32 v161, v44
	v_fma_f32 v44, v47, s25, -v147
	v_exp_f32_e32 v162, v44
	v_fma_f32 v44, v48, s25, -v147
	v_exp_f32_e32 v61, v44
	v_fma_f32 v44, v49, s25, -v147
	v_mfma_f32_32x32x16_bf16 v[172:187], v[236:239], v[80:83], v[172:187]
	v_fma_f32 v40, v43, s25, -v147
	v_exp_f32_e32 v63, v44
	ds_read_b128 v[44:47], v146 offset:13408
	v_exp_f32_e32 v158, v40
	v_cvt_pk_bf16_f32 v40, v67, v155
	v_cvt_pk_bf16_f32 v41, v66, v154
	v_cvt_pk_bf16_f32 v42, v157, v159
	v_cvt_pk_bf16_f32 v43, v156, v158
	v_fma_f32 v48, v50, s25, -v147
	s_waitcnt lgkmcnt(1)
	v_mfma_f32_32x32x16_bf16 v[4:19], v[36:39], v[40:43], v[4:19]
	v_fma_f32 v36, v51, s25, -v147
	v_exp_f32_e32 v60, v48
	v_exp_f32_e32 v62, v36
	v_mfma_f32_32x32x16_bf16 v[172:187], v[240:243], v[76:79], v[172:187]
	v_cvt_pk_bf16_f32 v36, v161, v163
	v_cvt_pk_bf16_f32 v37, v160, v162
	v_cvt_pk_bf16_f32 v38, v61, v63
	v_cvt_pk_bf16_f32 v39, v60, v62
	v_add_f32_e32 v48, v164, v165
	s_waitcnt lgkmcnt(0)
	v_mfma_f32_32x32x16_bf16 v[4:19], v[44:47], v[36:39], v[4:19]
	ds_read_b128 v[44:47], v146 offset:17920
	v_add_f32_e32 v164, 0, v48
	ds_read_b128 v[48:51], v146 offset:17952
	v_add_f32_e32 v165, v166, v167
	s_add_u32 s12, s12, 0x1000
	s_addc_u32 s13, s13, 0
	v_lshl_add_u64 v[132:133], v[132:133], 0, s[18:19]
	s_waitcnt lgkmcnt(1)
	v_mfma_f32_32x32x16_bf16 v[20:35], v[44:47], v[52:55], v[20:35]
	v_add_f32_e32 v44, v165, v164
	v_add_f32_e32 v45, v168, v169
	v_mfma_f32_32x32x16_bf16 v[172:187], v[244:247], v[84:87], v[172:187]
	v_add_f32_e32 v44, v45, v44
	v_add_f32_e32 v45, v170, v171
	v_add_f32_e32 v54, v45, v44
	ds_read_b128 v[44:47], v146 offset:17984
	v_pk_add_f32 v[52:53], v[148:149], v[150:151]
	s_waitcnt lgkmcnt(1)
	v_mfma_f32_32x32x16_bf16 v[20:35], v[48:51], v[56:59], v[20:35]
	v_add_f32_e32 v48, v53, v54
	v_add_f32_e32 v50, v52, v48
	v_add_f32_e64 v48, v152, v64
	v_add_f32_e64 v49, v153, v65
	v_add_f32_e64 v52, v66, v154
	v_mfma_f32_32x32x16_bf16 v[172:187], v[252:255], v[88:91], v[172:187]
	v_add_f32_e64 v53, v67, v155
	v_add_f32_e32 v49, v49, v50
	v_add_f32_e32 v54, v48, v49
	ds_read_b128 v[48:51], v146 offset:18016
	s_waitcnt lgkmcnt(1)
	v_mfma_f32_32x32x16_bf16 v[20:35], v[44:47], v[40:43], v[20:35]
	v_add_f32_e32 v40, v53, v54
	v_add_f32_e32 v42, v52, v40
	v_add_f32_e64 v40, v156, v158
	v_add_f32_e64 v41, v157, v159
	v_add_f32_e32 v41, v41, v42
	v_add_f32_e32 v44, v40, v41
	v_pk_add_f32 v[40:41], v[160:161], v[162:163]
	s_waitcnt lgkmcnt(0)
	v_mfma_f32_32x32x16_bf16 v[20:35], v[48:51], v[36:39], v[20:35]
	v_add_f32_e32 v36, v41, v44
	v_add_f32_e64 v42, v60, v62
	v_add_f32_e64 v43, v61, v63
	v_add_f32_e32 v36, v40, v36
	v_add_f32_e32 v36, v43, v36
	v_add_f32_e32 v36, v42, v36
	v_add_f32_e32 v127, v127, v36
	v_lshl_add_u64 v[134:135], v[134:135], 0, s[20:21]
	v_max_f32_e32 v156, v189, v189
	v_max_f32_e32 v157, v188, v188
	v_max_f32_e32 v156, v157, v156
	v_max3_f32 v148, v156, v190, v191
	v_max3_f32 v148, v148, v192, v193
	v_max3_f32 v148, v148, v194, v195
	v_max3_f32 v148, v148, v196, v197
	v_max3_f32 v148, v148, v198, v199
	v_max3_f32 v148, v148, v200, v201
	v_max3_f32 v148, v148, v202, v203
	v_max3_f32 v148, v148, v172, v173
	v_max3_f32 v148, v148, v174, v175
	v_max3_f32 v148, v148, v176, v177
	v_max3_f32 v148, v148, v178, v179
	v_max3_f32 v148, v148, v180, v181
	v_max3_f32 v148, v148, v182, v183
	v_max3_f32 v148, v148, v184, v185
	v_max3_f32 v148, v148, v186, v187
	ds_bpermute_b32 v149, v125, v148
	s_waitcnt lgkmcnt(0)
	v_max_f32_e32 v149, v149, v149
	v_max_f32_e32 v148, v148, v149
	v_mul_f32_e32 v148, 0x3e16c740, v148
	v_add_f32_e32 v149, 0x40c00000, v147
	v_cmp_gt_f32_e32 vcc, v148, v149
	s_cbranch_vccz .Lattn_norescale_A
; __device__ __forceinline__ void phase_attn(CP& p, char* smem, int vid0, int grid) {
;     ...
;       if (__builtin_amdgcn_ballot_w64(mcand > mrun + 6.0f) != 0ull) {
;         const float mnew_ = fmaxf(mrun, mcand);
;         const float alpha = __builtin_amdgcn_exp2f(mrun - mnew_);
;         mrun = mnew_;
;         lrun *= alpha;
; #pragma unroll
;         for (int i = 0; i < 16; ++i) { oacc[0][i] *= alpha; oacc[1][i] *= alpha; }
;       }
	v_max_f32_e32 v148, v148, v148
	v_max_f32_e32 v149, v147, v147
	v_max_f32_e32 v149, v149, v148
	v_sub_f32_e32 v147, v147, v149
	v_exp_f32_e32 v148, v147
	v_mov_b32_e32 v147, v149
	v_pk_mul_f32 v[34:35], v[34:35], v[148:149] op_sel_hi:[1,0]
	v_pk_mul_f32 v[32:33], v[32:33], v[148:149] op_sel_hi:[1,0]
	v_pk_mul_f32 v[30:31], v[30:31], v[148:149] op_sel_hi:[1,0]
	v_pk_mul_f32 v[28:29], v[28:29], v[148:149] op_sel_hi:[1,0]
	v_pk_mul_f32 v[26:27], v[26:27], v[148:149] op_sel_hi:[1,0]
	v_pk_mul_f32 v[24:25], v[24:25], v[148:149] op_sel_hi:[1,0]
	v_pk_mul_f32 v[22:23], v[22:23], v[148:149] op_sel_hi:[1,0]
	v_pk_mul_f32 v[20:21], v[20:21], v[148:149] op_sel_hi:[1,0]
	v_pk_mul_f32 v[18:19], v[18:19], v[148:149] op_sel_hi:[1,0]
	v_pk_mul_f32 v[16:17], v[16:17], v[148:149] op_sel_hi:[1,0]
	v_pk_mul_f32 v[14:15], v[14:15], v[148:149] op_sel_hi:[1,0]
	v_pk_mul_f32 v[12:13], v[12:13], v[148:149] op_sel_hi:[1,0]
	v_pk_mul_f32 v[10:11], v[10:11], v[148:149] op_sel_hi:[1,0]
	v_pk_mul_f32 v[8:9], v[8:9], v[148:149] op_sel_hi:[1,0]
	v_pk_mul_f32 v[6:7], v[6:7], v[148:149] op_sel_hi:[1,0]
	v_pk_mul_f32 v[4:5], v[4:5], v[148:149] op_sel_hi:[1,0]
	v_mul_f32_e32 v127, v127, v148
.Lattn_norescale_A:
	v_xor_b32_e32 v138, 0x8000, v138
	v_xor_b32_e32 v139, 0x8000, v139
	v_xor_b32_e32 v140, 0x8000, v140
	v_xor_b32_e32 v145, 0x8000, v145
	v_xor_b32_e32 v146, 0x8000, v146
	s_branch .Lattn_body_B
.Lattn_tail:
	s_branch .LBB0_2024

; __global__ void __launch_bounds__(512, 2) mega(P p_arg) {
;   __shared__ __attribute__((aligned(16))) char smem[LDS_BYTES];
	.amdhsa_kernel _Z4mega1P
		.amdhsa_group_segment_fixed_size 163840
		.amdhsa_private_segment_fixed_size 0
		.amdhsa_kernarg_size 816
		.amdhsa_user_sgpr_count 2
		.amdhsa_user_sgpr_dispatch_ptr 0
		.amdhsa_user_sgpr_queue_ptr 0
		.amdhsa_user_sgpr_kernarg_segment_ptr 1
		.amdhsa_user_sgpr_dispatch_id 0
		.amdhsa_user_sgpr_kernarg_preload_length 0
		.amdhsa_user_sgpr_kernarg_preload_offset 0
		.amdhsa_user_sgpr_private_segment_size 0
		.amdhsa_uses_dynamic_stack 0
		.amdhsa_enable_private_segment 0
		.amdhsa_system_sgpr_workgroup_id_x 1
		.amdhsa_system_sgpr_workgroup_id_y 0
		.amdhsa_system_sgpr_workgroup_id_z 0
		.amdhsa_system_sgpr_workgroup_info 0
		.amdhsa_system_vgpr_workitem_id 2
		.amdhsa_next_free_vgpr 256
		.amdhsa_next_free_sgpr 98
		.amdhsa_accum_offset 256
		.amdhsa_reserve_vcc 1
		.amdhsa_float_round_mode_32 0
		.amdhsa_float_round_mode_16_64 0
		.amdhsa_float_denorm_mode_32 3
		.amdhsa_float_denorm_mode_16_64 3
		.amdhsa_dx10_clamp 1
		.amdhsa_ieee_mode 1
		.amdhsa_fp16_overflow 0
		.amdhsa_tg_split 0
		.amdhsa_exception_fp_ieee_invalid_op 0
		.amdhsa_exception_fp_denorm_src 0
		.amdhsa_exception_fp_ieee_div_zero 0
		.amdhsa_exception_fp_ieee_overflow 0
		.amdhsa_exception_fp_ieee_underflow 0
		.amdhsa_exception_fp_ieee_inexact 0
		.amdhsa_exception_int_div_zero 0
	.end_amdhsa_kernel

; __global__ void __launch_bounds__(512, 2) mega(P p_arg) {
;   __shared__ __attribute__((aligned(16))) char smem[LDS_BYTES];
amdhsa.kernels:
  - .agpr_count:     0
    .args:
      - .offset:         0
        .size:           560
        .value_kind:     by_value
      - .offset:         560
        .size:           4
        .value_kind:     hidden_block_count_x
      - .offset:         564
        .size:           4
        .value_kind:     hidden_block_count_y
      - .offset:         568
        .size:           4
        .value_kind:     hidden_block_count_z
      - .offset:         572
        .size:           2
        .value_kind:     hidden_group_size_x
      - .offset:         574
        .size:           2
        .value_kind:     hidden_group_size_y
      - .offset:         576
        .size:           2
        .value_kind:     hidden_group_size_z
      - .offset:         578
        .size:           2
        .value_kind:     hidden_remainder_x
      - .offset:         580
        .size:           2
        .value_kind:     hidden_remainder_y
      - .offset:         582
        .size:           2
        .value_kind:     hidden_remainder_z
      - .offset:         600
        .size:           8
        .value_kind:     hidden_global_offset_x
      - .offset:         608
        .size:           8
        .value_kind:     hidden_global_offset_y
      - .offset:         616
        .size:           8
        .value_kind:     hidden_global_offset_z
      - .offset:         624
        .size:           2
        .value_kind:     hidden_grid_dims
      - .offset:         648
        .size:           8
        .value_kind:     hidden_multigrid_sync_arg
    .group_segment_fixed_size: 163840
    .kernarg_segment_align: 8
    .kernarg_segment_size: 816
    .language:       OpenCL C
    .language_version:
      - 2
      - 0
    .max_flat_workgroup_size: 512
    .name:           _Z4mega1P
    .private_segment_fixed_size: 0
    .sgpr_count:     104
    .sgpr_spill_count: 20
    .symbol:         _Z4mega1P.kd
    .uniform_work_group_size: 1
    .uses_dynamic_stack: false
    .vgpr_count:     256
    .vgpr_spill_count: 0
    .wavefront_size: 64
